# code placement: fused lean tile's first LDS read on a 64-byte boundary (48 bytes of never-executed padding in front of the interval loop)
# baseline (speedup 1.0000x reference)
.LBB0_640:
	v_mov_b32_e32 v178, v184
	v_mov_b32_e32 v179, v182
	s_cmp_gt_i32 s68, s69
	.p2align 8
	s_cbranch_scc1 .LBB0_681
	v_mov_b32_e32 v86, v84
	v_mov_b32_e32 v87, v84
	v_mov_b32_e32 v88, v84
	v_mov_b32_e32 v89, v84
	v_mov_b32_e32 v90, v84
	v_mov_b32_e32 v91, v84
	v_mov_b32_e32 v92, v84
	v_mov_b32_e32 v93, v84
	v_mov_b32_e32 v94, v84
	v_mov_b32_e32 v95, v84
	v_mov_b32_e32 v96, v84
	v_mov_b32_e32 v97, v84
	v_mov_b32_e32 v98, v84
	v_mov_b32_e32 v99, v84
	v_mov_b32_e32 v16, v2
	v_mov_b32_e32 v17, v2
	v_mov_b32_e32 v85, v84
	s_cmp_eq_u32 s11, s61
	v_mov_b32_e32 v3, v2
	v_mov_b32_e32 v4, v2
	v_mov_b32_e32 v5, v2
	v_mov_b32_e32 v6, v2
	v_mov_b32_e32 v7, v2
	v_mov_b32_e32 v8, v2
	v_mov_b32_e32 v9, v2
	v_mov_b32_e32 v10, v2
	v_mov_b32_e32 v11, v2
	v_mov_b32_e32 v12, v2
	v_mov_b32_e32 v13, v2
	v_mov_b32_e32 v14, v2
	v_mov_b32_e32 v15, v2
	v_mov_b32_e32 v181, 0
	v_mov_b64_e32 v[100:101], v[98:99]
	v_mov_b64_e32 v[82:83], v[16:17]
	v_mov_b64_e32 v[66:67], v[16:17]
	s_cselect_b64 s[34:35], -1, 0
	s_add_i32 s74, s21, 0
	s_add_i32 s75, s38, 0
	v_mov_b32_e32 v186, v184
	v_mov_b32_e32 v187, v184
	v_mov_b32_e32 v188, v182
	v_mov_b32_e32 v189, v182
	v_mov_b32_e32 v20, v2
	v_mov_b32_e32 v21, v2
	v_mov_b32_e32 v22, v2
	v_mov_b32_e32 v23, v2
	v_mov_b32_e32 v24, v2
	v_mov_b32_e32 v25, v2
	v_mov_b32_e32 v26, v2
	v_mov_b32_e32 v27, v2
	v_mov_b32_e32 v28, v2
	v_mov_b32_e32 v29, v2
	v_mov_b32_e32 v30, v2
	v_mov_b32_e32 v31, v2
	v_mov_b32_e32 v32, v2
	v_mov_b32_e32 v33, v2
	v_mov_b32_e32 v34, v2
	v_mov_b32_e32 v35, v2
	v_mov_b32_e32 v36, v2
	v_mov_b32_e32 v37, v2
	v_mov_b32_e32 v38, v2
	v_mov_b32_e32 v39, v2
	v_mov_b32_e32 v40, v2
	v_mov_b32_e32 v41, v2
	v_mov_b32_e32 v42, v2
	v_mov_b32_e32 v43, v2
	v_mov_b32_e32 v44, v2
	v_mov_b32_e32 v45, v2
	v_mov_b32_e32 v46, v2
	v_mov_b32_e32 v47, v2
	v_mov_b32_e32 v48, v2
	v_mov_b32_e32 v49, v2
	v_mov_b32_e32 v50, v2
	v_mov_b32_e32 v51, v2
	v_mov_b32_e32 v180, v181
	v_mov_b64_e32 v[98:99], v[96:97]
	v_mov_b64_e32 v[96:97], v[94:95]
	v_mov_b64_e32 v[94:95], v[92:93]
	v_mov_b64_e32 v[92:93], v[90:91]
	v_mov_b64_e32 v[90:91], v[88:89]
	v_mov_b64_e32 v[88:89], v[86:87]
	v_mov_b64_e32 v[86:87], v[84:85]
	v_mov_b64_e32 v[80:81], v[14:15]
	v_mov_b64_e32 v[78:79], v[12:13]
	v_mov_b64_e32 v[76:77], v[10:11]
	v_mov_b64_e32 v[74:75], v[8:9]
	v_mov_b64_e32 v[72:73], v[6:7]
	v_mov_b64_e32 v[70:71], v[4:5]
	v_mov_b64_e32 v[68:69], v[2:3]
	v_mov_b64_e32 v[64:65], v[14:15]
	v_mov_b64_e32 v[62:63], v[12:13]
	v_mov_b64_e32 v[60:61], v[10:11]
	v_mov_b64_e32 v[58:59], v[8:9]
	v_mov_b64_e32 v[56:57], v[6:7]
	v_mov_b64_e32 v[54:55], v[4:5]
	v_mov_b64_e32 v[52:53], v[2:3]
	s_waitcnt vmcnt(0)
	s_branch .LBB0_643
	s_nop 0
	s_nop 0
	s_nop 0
	s_nop 0
	s_nop 0
	s_nop 0
	s_nop 0
	s_nop 0
	s_nop 0
	s_nop 0
	s_nop 0
	s_nop 0
